# phase 15: tiles straddling the causal edge (queries' own block, selected and window) take a masked variant of the hand-scheduled fast path instead of the compiler's path
# speedup vs baseline: 1.0166x; 1.0095x over previous
; __device__ __forceinline__ void nsa_qk(f32x4 (&s)[2][4], const u16* sK, const bf16x8 (&qf)[2][2], int fr, int fq) {
; #pragma unroll
;   for (int mt = 0; mt < 4; ++mt) {
;     s[0][mt] = (f32x4){0.f, 0.f, 0.f, 0.f}; s[1][mt] = (f32x4){0.f, 0.f, 0.f, 0.f};
; #pragma unroll
;     for (int ks = 0; ks < 2; ++ks) {
;       bf16x8 kf = *(const bf16x8*)(sK + (mt * 16 + fr) * LDSP + ks * 32 + fq * 8);
;       s[0][mt] = mfma16(kf, qf[0][ks], s[0][mt]);
;       s[1][mt] = mfma16(kf, qf[1][ks], s[1][mt]);
; __device__ __forceinline__ void phase_nsa_sw(const Params& p, u16* sm) {
;     ...
;       nsa_qk(s, cK, qf, fr, fq);
;       {
;         const bool is_sel = (v < 64);
;         const int kt = is_sel ? v : v - 64;
;         const bool lv = is_sel ? (bool)((mymask >> v) & 1ull) : true;
;         const bool masked = is_sel ? (v == (t0 >> 6)) : !((64 * kt + 63 <= t0) && (64 * kt >= t0 - 480));
;         if (masked) {
.Lfp15m_body:
	s_and_b32 s21, s14, 63
	s_lshl_b32 s21, s21, 6
	s_sub_i32 s21, s44, s21
	s_add_i32 s8, s89, 0xffffff80
	s_and_b32 s9, s8, 0x100
	s_and_b32 s8, s8, 0x80
	s_mulk_i32 s8, 0x90
	s_mulk_i32 s9, 0x120
	s_add_i32 s8, s8, s9
	v_add_u32_e32 v2, s8, v218
	s_cmp_gt_i32 s14, 63
	ds_read_b128 v[136:139], v2
	ds_read_b128 v[140:143], v2 offset:64
	ds_read_b128 v[144:147], v2 offset:2304
	ds_read_b128 v[148:151], v2 offset:2368
	ds_read_b128 v[152:155], v2 offset:4608
	ds_read_b128 v[156:159], v2 offset:4672
	ds_read_b128 v[160:163], v2 offset:6912
	ds_read_b128 v[164:167], v2 offset:6976
	s_cbranch_scc1 .Lfp15m_lvall
	s_lshl_b64 s[10:11], 1, s14
	v_and_b32_e32 v1, s10, v210
	v_and_b32_e32 v3, s11, v211
	v_or_b32_e32 v1, v1, v3
	v_cmp_ne_u32_e32 vcc, 0, v1
	s_mov_b64 s[30:31], vcc
	s_branch .Lfp15m_lvdone

; __device__ __forceinline__ void nsa_qk(f32x4 (&s)[2][4], const u16* sK, const bf16x8 (&qf)[2][2], int fr, int fq) {
; #pragma unroll
;   for (int mt = 0; mt < 4; ++mt) {
;     s[0][mt] = (f32x4){0.f, 0.f, 0.f, 0.f}; s[1][mt] = (f32x4){0.f, 0.f, 0.f, 0.f};
; #pragma unroll
;     for (int ks = 0; ks < 2; ++ks) {
;       bf16x8 kf = *(const bf16x8*)(sK + (mt * 16 + fr) * LDSP + ks * 32 + fq * 8);
;       s[0][mt] = mfma16(kf, qf[0][ks], s[0][mt]);
;       s[1][mt] = mfma16(kf, qf[1][ks], s[1][mt]);
;     }
;   }
; }
; template <bool MASKED>
; __device__ __forceinline__ void nsa_online_step(NsaState& st, f32x4 (&s)[2][4], unsigned vmask, bool lanevalid, const u16* sV, int fr, int fq) {
;     ...
;   for (int hh = 0; hh < 2; ++hh) {
;     float tmax = -1e30f;
;     if (MASKED) {
; #pragma unroll
;       for (int mt = 0; mt < 4; ++mt)
; #pragma unroll
;         for (int j = 0; j < 4; ++j) {
;           const float sc = ((vmask >> (mt * 4 + j)) & 1u) ? s[hh][mt][j] : -1e30f;
;           s[hh][mt][j] = sc;
;           tmax = fmaxf(tmax, sc);
;         }
;     } else {
; #pragma unroll
;       for (int mt = 0; mt < 4; ++mt)
; #pragma unroll
;         for (int j = 0; j < 4; ++j) tmax = fmaxf(tmax, s[hh][mt][j]);
;       tmax = lanevalid ? tmax : -1e30f;
;     }
;     tmax = fmaxf(tmax, __shfl_xor(tmax, 16));
;     tmax = fmaxf(tmax, __shfl_xor(tmax, 32));
;     const bool upd = tmax > st.m[hh] + DEFER;
;     if (__ballot(upd) != 0ull) {
.Lfp15m_lvdone:
	s_mov_b32 s20, 0x3e38aa3b
	s_waitcnt lgkmcnt(4)
	v_mfma_f32_16x16x32_bf16 v[68:71], v[136:139], v[4:7], 0
	v_mfma_f32_16x16x32_bf16 v[72:75], v[144:147], v[4:7], 0
	v_mfma_f32_16x16x32_bf16 v[68:71], v[140:143], v[8:11], v[68:71]
	v_mfma_f32_16x16x32_bf16 v[72:75], v[148:151], v[8:11], v[72:75]
	s_waitcnt lgkmcnt(0)
	ds_read_b128 v[28:31], v2 offset:9216
	ds_read_b128 v[36:39], v2 offset:11520
	ds_read_b128 v[44:47], v2 offset:13824
	ds_read_b128 v[124:127], v2 offset:16128
	ds_read_b128 v[32:35], v2 offset:9280
	ds_read_b128 v[40:43], v2 offset:11584
	ds_read_b128 v[120:123], v2 offset:13888
	ds_read_b128 v[128:131], v2 offset:16192
	v_mfma_f32_16x16x32_bf16 v[76:79], v[152:155], v[4:7], 0
	v_mfma_f32_16x16x32_bf16 v[80:83], v[160:163], v[4:7], 0
	v_mfma_f32_16x16x32_bf16 v[76:79], v[156:159], v[8:11], v[76:79]
	v_mfma_f32_16x16x32_bf16 v[80:83], v[164:167], v[8:11], v[80:83]
	v_mfma_f32_16x16x32_bf16 v[84:87], v[136:139], v[12:15], 0
	v_mfma_f32_16x16x32_bf16 v[88:91], v[144:147], v[12:15], 0
	v_mfma_f32_16x16x32_bf16 v[84:87], v[140:143], v[16:19], v[84:87]
	v_mfma_f32_16x16x32_bf16 v[88:91], v[148:151], v[16:19], v[88:91]
	v_mfma_f32_16x16x32_bf16 v[92:95], v[152:155], v[12:15], 0
	v_mfma_f32_16x16x32_bf16 v[96:99], v[160:163], v[12:15], 0
	v_mfma_f32_16x16x32_bf16 v[92:95], v[156:159], v[16:19], v[92:95]
	v_mfma_f32_16x16x32_bf16 v[96:99], v[164:167], v[16:19], v[96:99]
	v_readfirstlane_b32 s13, v231
	s_add_i32 s11, s42, 3
	s_and_b32 s12, s11, 1
	s_mulk_i32 s12, 0x4800
	s_and_b32 s18, s11, 2
	s_mul_i32 s18, s18, 0x9000
	s_add_i32 s12, s12, s18
	s_add_i32 s13, s13, -1
	s_min_i32 s11, s11, s13
	v_readlane_b32 s18, v24, s11
	v_readlane_b32 s19, v25, s11
	s_cmp_lt_u32 s11, 64
	s_cselect_b32 s11, s18, s19
	s_cmp_lt_i32 s11, 64
	s_cselect_b32 s14, s62, s78
	s_cselect_b32 s15, s63, s79
	s_cselect_b32 s16, s66, s80
	s_cselect_b32 s17, s67, s81
	s_and_b32 s13, s11, 63
	s_lshl_b32 s18, s13, 14
	s_lshl_b32 s13, s13, 7
	s_add_u32 s14, s14, s18
	s_addc_u32 s15, s15, 0
	s_add_u32 s16, s16, s13
	s_addc_u32 s17, s17, 0
	v_readfirstlane_b32 s18, v251
	v_readfirstlane_b32 s19, v252
	s_nop 0
	s_add_u32 s18, s18, s12
	s_mov_b32 m0, s18
	s_add_u32 s18, s18, 0x2400
	global_load_lds_dwordx4 v248, s[14:15]
	s_mov_b32 m0, s18
	s_cmp_ge_u32 s19, 0x2400
	global_load_lds_dwordx4 v249, s[16:17]
	s_cselect_b32 s14, s16, s14
	s_cselect_b32 s15, s17, s15
	s_add_u32 s19, s19, s12
	s_mov_b32 m0, s19
	s_mov_b64 exec, 0xffff
	global_load_lds_dwordx4 v250, s[14:15]
	s_mov_b64 exec, -1
	v_max3_f32 v1, v68, v69, v70
	v_max3_f32 v1, v1, v71, v72
	v_max3_f32 v1, v1, v73, v74
	v_max3_f32 v1, v1, v75, v76
	v_max3_f32 v1, v1, v77, v78
	v_max3_f32 v1, v1, v79, v80
	v_max3_f32 v1, v1, v81, v82
	v_max_f32_e32 v1, v1, v83
	v_and_b32_e32 v160, 0x100, v192
	v_and_b32_e32 v161, 15, v192
	v_and_b32_e32 v162, 0x30, v192
	v_lshrrev_b32_e32 v160, 4, v160
	v_lshrrev_b32_e32 v162, 1, v162
	v_add_u32_e32 v160, v160, v161
	v_mov_b32_e32 v164, 0xffff
	v_sub_u32_e32 v160, v160, v162
	v_mov_b32_e32 v165, 0xffff0000
	v_add_u32_e32 v160, s21, v160
	v_subrev_u32_e32 v161, 0, v160
	v_cmp_gt_u32_e32 vcc, 0x200, v161
	v_add_u32_e32 v162, -1, v161
	s_nop 0
	v_cndmask_b32_e32 v152, 0, v164, vcc
	v_cmp_gt_u32_e32 vcc, 0x200, v162
	s_nop 1
	v_cndmask_b32_e32 v163, 0, v165, vcc
	v_or_b32_e32 v152, v152, v163
	v_subrev_u32_e32 v161, 2, v160
	v_cmp_gt_u32_e32 vcc, 0x200, v161
	v_add_u32_e32 v162, -1, v161
	s_nop 0
	v_cndmask_b32_e32 v153, 0, v164, vcc
	v_cmp_gt_u32_e32 vcc, 0x200, v162
	s_nop 1
	v_cndmask_b32_e32 v163, 0, v165, vcc
	v_or_b32_e32 v153, v153, v163
	v_subrev_u32_e32 v161, 4, v160
	v_cmp_gt_u32_e32 vcc, 0x200, v161
	v_add_u32_e32 v162, -1, v161
	s_nop 0
	v_cndmask_b32_e32 v154, 0, v164, vcc
	v_cmp_gt_u32_e32 vcc, 0x200, v162
	s_nop 1
	v_cndmask_b32_e32 v163, 0, v165, vcc
	v_or_b32_e32 v154, v154, v163
	v_subrev_u32_e32 v161, 6, v160
	v_cmp_gt_u32_e32 vcc, 0x200, v161
	v_add_u32_e32 v162, -1, v161
	s_nop 0
	v_cndmask_b32_e32 v155, 0, v164, vcc
	v_cmp_gt_u32_e32 vcc, 0x200, v162
	s_nop 1
	v_cndmask_b32_e32 v163, 0, v165, vcc
	v_or_b32_e32 v155, v155, v163
	v_subrev_u32_e32 v161, 32, v160
	v_cmp_gt_u32_e32 vcc, 0x200, v161
	v_add_u32_e32 v162, -1, v161
	s_nop 0
	v_cndmask_b32_e32 v156, 0, v164, vcc
	v_cmp_gt_u32_e32 vcc, 0x200, v162
	s_nop 1
	v_cndmask_b32_e32 v163, 0, v165, vcc
	v_or_b32_e32 v156, v156, v163
	v_subrev_u32_e32 v161, 34, v160
	v_cmp_gt_u32_e32 vcc, 0x200, v161
	v_add_u32_e32 v162, -1, v161
	s_nop 0
	v_cndmask_b32_e32 v157, 0, v164, vcc
	v_cmp_gt_u32_e32 vcc, 0x200, v162
	s_nop 1
	v_cndmask_b32_e32 v163, 0, v165, vcc
	v_or_b32_e32 v157, v157, v163
	v_subrev_u32_e32 v161, 36, v160
	v_cmp_gt_u32_e32 vcc, 0x200, v161
	v_add_u32_e32 v162, -1, v161
	s_nop 0
	v_cndmask_b32_e32 v158, 0, v164, vcc
	v_cmp_gt_u32_e32 vcc, 0x200, v162
	s_nop 1
	v_cndmask_b32_e32 v163, 0, v165, vcc
	v_or_b32_e32 v158, v158, v163
	v_subrev_u32_e32 v161, 38, v160
	v_cmp_gt_u32_e32 vcc, 0x200, v161
	v_add_u32_e32 v162, -1, v161
	s_nop 0
	v_cndmask_b32_e32 v159, 0, v164, vcc
	v_cmp_gt_u32_e32 vcc, 0x200, v162
	s_nop 1
	v_cndmask_b32_e32 v163, 0, v165, vcc
	v_or_b32_e32 v159, v159, v163
	v_add_f32_e32 v168, 0x42317218, v234
	v_cmp_gt_f32_e32 vcc, v1, v168
	s_and_b64 s[8:9], vcc, s[30:31]
	s_cbranch_scc1 .Lfp15m_upd0
; template <bool MASKED>
; __device__ __forceinline__ void nsa_online_step(NsaState& st, f32x4 (&s)[2][4], unsigned vmask, bool lanevalid, const u16* sV, int fr, int fq) {
;     ...
;     const float nb = -st.m[hh] * SM_C;
; #pragma unroll
;     for (int k2 = 0; k2 < 2; ++k2) {
;       uint32_t pw[4];
; #pragma unroll
;       for (int e2 = 0; e2 < 4; ++e2) {
;         const int mt = 2 * k2 + (e2 >> 1), j = (e2 & 1) * 2;
;         float p0 = __builtin_amdgcn_exp2f(__builtin_fmaf(s[hh][mt][j], SM_C, nb));
;         float p1 = __builtin_amdgcn_exp2f(__builtin_fmaf(s[hh][mt][j + 1], SM_C, nb));
;         if (MASKED) {
;           p0 = ((vmask >> (mt * 4 + j)) & 1u) ? p0 : 0.f;
;           p1 = ((vmask >> (mt * 4 + j + 1)) & 1u) ? p1 : 0.f;
;         }
;         pw[e2] = pack2(p0, p1);
;         if (!MASKED) pw[e2] &= lmask;
;       }
;       pf[hh][k2] = mk_frag(pw[0], pw[1], pw[2], pw[3]);
.Lfp15m_noupd0:
	v_mul_f32_e32 v2, 0xbe38aa3b, v234
	v_cndmask_b32_e64 v2, v221, v2, s[30:31]
	v_pk_fma_f32 v[136:137], v[68:69], s[20:21], v[2:3] op_sel_hi:[1,0,0]
	v_pk_fma_f32 v[138:139], v[70:71], s[20:21], v[2:3] op_sel_hi:[1,0,0]
	v_exp_f32_e32 v136, v136
	v_exp_f32_e32 v137, v137
	v_exp_f32_e32 v138, v138
	v_exp_f32_e32 v139, v139
	v_pk_fma_f32 v[140:141], v[72:73], s[20:21], v[2:3] op_sel_hi:[1,0,0]
	v_pk_fma_f32 v[142:143], v[74:75], s[20:21], v[2:3] op_sel_hi:[1,0,0]
	v_cvt_pk_bf16_f32 v236, v136, v137
	v_cvt_pk_bf16_f32 v237, v138, v139
	v_and_b32_e32 v236, v236, v152
	v_and_b32_e32 v237, v237, v153
	v_exp_f32_e32 v140, v140
	v_exp_f32_e32 v141, v141
	v_exp_f32_e32 v142, v142
	v_exp_f32_e32 v143, v143
	v_pk_fma_f32 v[144:145], v[76:77], s[20:21], v[2:3] op_sel_hi:[1,0,0]
	v_pk_fma_f32 v[146:147], v[78:79], s[20:21], v[2:3] op_sel_hi:[1,0,0]
	v_cvt_pk_bf16_f32 v238, v140, v141
	v_cvt_pk_bf16_f32 v239, v142, v143
	v_and_b32_e32 v238, v238, v154
	v_and_b32_e32 v239, v239, v155
	v_exp_f32_e32 v144, v144
	v_exp_f32_e32 v145, v145
	v_exp_f32_e32 v146, v146
	v_exp_f32_e32 v147, v147
	v_pk_fma_f32 v[148:149], v[80:81], s[20:21], v[2:3] op_sel_hi:[1,0,0]
	v_pk_fma_f32 v[150:151], v[82:83], s[20:21], v[2:3] op_sel_hi:[1,0,0]
	v_cvt_pk_bf16_f32 v240, v144, v145
	v_cvt_pk_bf16_f32 v241, v146, v147
	v_and_b32_e32 v240, v240, v156
	v_and_b32_e32 v241, v241, v157
	v_exp_f32_e32 v148, v148
	v_exp_f32_e32 v149, v149
	v_exp_f32_e32 v150, v150
	v_exp_f32_e32 v151, v151
.Lfp15m_xend:
	v_readfirstlane_b32 s8, v192
	v_cvt_pk_bf16_f32 v242, v148, v149
	v_cvt_pk_bf16_f32 v243, v150, v151
	v_and_b32_e32 v242, v242, v158
	v_and_b32_e32 v243, v243, v159
	s_cmp_lt_u32 s8, 0x100
	s_cbranch_scc1 .Lfp15m_ystart
	v_readfirstlane_b32 s9, v231
	s_add_i32 s10, s42, 1
	s_cmp_ge_i32 s10, s9
	s_cbranch_scc1 .Lfp15m_ystart
	s_waitcnt vmcnt(6)
	s_waitcnt lgkmcnt(0)
	s_barrier

; template <bool MASKED>
; __device__ __forceinline__ void nsa_online_step(NsaState& st, f32x4 (&s)[2][4], unsigned vmask, bool lanevalid, const u16* sV, int fr, int fq) {
;     ...
;     const float nb = -st.m[hh] * SM_C;
; #pragma unroll
;     for (int k2 = 0; k2 < 2; ++k2) {
;       uint32_t pw[4];
; #pragma unroll
;       for (int e2 = 0; e2 < 4; ++e2) {
;         const int mt = 2 * k2 + (e2 >> 1), j = (e2 & 1) * 2;
;         float p0 = __builtin_amdgcn_exp2f(__builtin_fmaf(s[hh][mt][j], SM_C, nb));
;         float p1 = __builtin_amdgcn_exp2f(__builtin_fmaf(s[hh][mt][j + 1], SM_C, nb));
;         if (MASKED) {
;           p0 = ((vmask >> (mt * 4 + j)) & 1u) ? p0 : 0.f;
;           p1 = ((vmask >> (mt * 4 + j + 1)) & 1u) ? p1 : 0.f;
;         }
;         pw[e2] = pack2(p0, p1);
;         if (!MASKED) pw[e2] &= lmask;
;       }
;       pf[hh][k2] = mk_frag(pw[0], pw[1], pw[2], pw[3]);
;       st.accL[hh] = mfma16(ones, pf[hh][k2], st.accL[hh]);
;     }
; #pragma unroll
;     for (int k2 = 0; k2 < 2; ++k2)
; #pragma unroll
;       for (int dm = 0; dm < 4; ++dm) {
;         const bf16x8 vf = *(const bf16x8*)(sV + (dm * 16 + fr) * LDSP + k2 * 32 + fq * 8);
;         st.acc[hh][dm] = mfma16(vf, pf[hh][k2], st.acc[hh][dm]);
;       }
.Lfp15m_noupd1:
	v_mul_f32_e32 v2, 0xbe38aa3b, v235
	v_cndmask_b32_e64 v2, v221, v2, s[30:31]
	v_pk_fma_f32 v[136:137], v[84:85], s[20:21], v[2:3] op_sel_hi:[1,0,0]
	v_pk_fma_f32 v[138:139], v[86:87], s[20:21], v[2:3] op_sel_hi:[1,0,0]
	v_exp_f32_e32 v136, v136
	v_exp_f32_e32 v137, v137
	v_exp_f32_e32 v138, v138
	v_mfma_f32_16x16x32_bf16 v[48:51], v[20:23], v[240:243], v[48:51]
	v_exp_f32_e32 v139, v139
	v_pk_fma_f32 v[140:141], v[88:89], s[20:21], v[2:3] op_sel_hi:[1,0,0]
	v_pk_fma_f32 v[142:143], v[90:91], s[20:21], v[2:3] op_sel_hi:[1,0,0]
	v_cvt_pk_bf16_f32 v244, v136, v137
	v_cvt_pk_bf16_f32 v245, v138, v139
	v_mfma_f32_16x16x32_bf16 v[52:55], v[32:35], v[240:243], v[52:55]
	v_and_b32_e32 v244, v244, v152
	v_and_b32_e32 v245, v245, v153
	v_exp_f32_e32 v140, v140
	v_exp_f32_e32 v141, v141
	v_exp_f32_e32 v142, v142
	v_mfma_f32_16x16x32_bf16 v[56:59], v[40:43], v[240:243], v[56:59]
	v_exp_f32_e32 v143, v143
	v_pk_fma_f32 v[144:145], v[92:93], s[20:21], v[2:3] op_sel_hi:[1,0,0]
	v_pk_fma_f32 v[146:147], v[94:95], s[20:21], v[2:3] op_sel_hi:[1,0,0]
	v_cvt_pk_bf16_f32 v246, v140, v141
	v_cvt_pk_bf16_f32 v247, v142, v143
	v_mfma_f32_16x16x32_bf16 v[60:63], v[120:123], v[240:243], v[60:63]
	v_and_b32_e32 v246, v246, v154
	v_and_b32_e32 v247, v247, v155
	v_exp_f32_e32 v144, v144
	v_exp_f32_e32 v145, v145
	v_exp_f32_e32 v146, v146
	v_mfma_f32_16x16x32_bf16 v[64:67], v[128:131], v[240:243], v[64:67]
	v_exp_f32_e32 v147, v147
	v_pk_fma_f32 v[148:149], v[96:97], s[20:21], v[2:3] op_sel_hi:[1,0,0]
	v_pk_fma_f32 v[150:151], v[98:99], s[20:21], v[2:3] op_sel_hi:[1,0,0]
	v_cvt_pk_bf16_f32 v100, v144, v145
	v_cvt_pk_bf16_f32 v101, v146, v147
	v_and_b32_e32 v100, v100, v156
	v_and_b32_e32 v101, v101, v157
	v_exp_f32_e32 v148, v148
	v_exp_f32_e32 v149, v149
	v_exp_f32_e32 v150, v150
	v_exp_f32_e32 v151, v151
	s_nop 0
	v_cvt_pk_bf16_f32 v102, v148, v149
	v_cvt_pk_bf16_f32 v103, v150, v151
	v_and_b32_e32 v102, v102, v158
	v_and_b32_e32 v103, v103, v159
	s_nop 0
	v_mfma_f32_16x16x32_bf16 v[132:135], v[20:23], v[244:247], v[132:135]
	v_mfma_f32_16x16x32_bf16 v[116:119], v[28:31], v[244:247], v[116:119]
	v_mfma_f32_16x16x32_bf16 v[112:115], v[36:39], v[244:247], v[112:115]
	v_mfma_f32_16x16x32_bf16 v[108:111], v[44:47], v[244:247], v[108:111]
	v_mfma_f32_16x16x32_bf16 v[104:107], v[124:127], v[244:247], v[104:107]
	v_mfma_f32_16x16x32_bf16 v[132:135], v[20:23], v[100:103], v[132:135]
	v_mfma_f32_16x16x32_bf16 v[116:119], v[32:35], v[100:103], v[116:119]
	v_mfma_f32_16x16x32_bf16 v[112:115], v[40:43], v[100:103], v[112:115]
	v_mfma_f32_16x16x32_bf16 v[108:111], v[120:123], v[100:103], v[108:111]
	v_mfma_f32_16x16x32_bf16 v[104:107], v[128:131], v[100:103], v[104:107]
	s_branch .Lfp15_tail
